# attention: s_setprio 1 while a wave is in its MFMA (PV+QK) segment, 0 in softmax segment; first item's fetch issued before the phase's LDS barrier
# speedup vs baseline: 1.0231x; 1.0009x over previous
.LBB0_316:
	v_readlane_b32 s4, v251, 48
	v_readlane_b32 s34, v253, 15
	v_mbcnt_lo_u32_b32 v0, -1, 0
	v_mbcnt_hi_u32_b32 v0, -1, v0
	s_lshr_b32 s36, s4, 2
	s_and_b32 s31, s4, 3
	s_lshr_b32 s29, s36, 3
	s_and_b32 s30, s36, 7
	s_lshr_b32 s34, s34, 6
	s_lshr_b32 s35, s34, 2
	v_and_b32_e32 v240, 31, v0
	v_lshrrev_b32_e32 v241, 5, v0
	v_lshl_add_u32 v247, s34, 6, v0
	v_lshrrev_b32_e32 v248, 4, v247
	v_and_b32_e32 v249, 15, v247
	v_lshlrev_b32_e32 v220, 11, v248
	v_lshl_add_u32 v220, v249, 4, v220
	v_mul_u32_u24_e32 v225, 0x190, v248
	v_lshl_add_u32 v225, v249, 4, v225
	v_lshrrev_b32_e32 v248, 3, v247
	v_and_b32_e32 v249, 7, v247
	v_lshlrev_b32_e32 v221, 7, v248
	v_lshl_add_u32 v221, v249, 4, v221
	v_mul_u32_u24_e32 v226, 0x190, v248
	v_lshl_add_u32 v226, v249, 4, v226
	v_add_u32_e32 v226, 0x100, v226
	v_mul_u32_u24_e32 v222, 0x8200, v248
	v_lshl_add_u32 v222, v249, 4, v222
	v_mul_u32_u24_e32 v227, 0x88, v248
	v_lshl_add_u32 v227, v249, 4, v227
	v_add_u32_e32 v227, 0x12c00, v227
	v_add_u32_e32 v228, 0x2200, v227
	v_lshlrev_b32_e32 v223, 5, v0
	v_lshlrev_b32_e32 v224, 2, v0
	v_add_u32_e32 v229, 0x1f800, v224
	v_mul_u32_u24_e32 v230, 0x190, v240
	v_lshl_add_u32 v230, v241, 4, v230
	v_mul_u32_u24_e32 v231, 0x88, v240
	v_lshl_add_u32 v231, v241, 3, v231
	v_add_u32_e32 v231, 0x12c00, v231
	v_lshlrev_b32_e32 v232, 4, v241
	v_add_u32_e32 v232, 0x1f800, v232
	v_xor_b32_e32 v233, 32, v0
	v_lshlrev_b32_e32 v233, 2, v233
	v_mov_b32_e32 v238, 0xf149f2ca
	s_mov_b32 s26, 0
	s_mul_i32 s38, s29, 0x810
	s_mul_i32 s36, s30, 0x180
	s_add_u32 s40, s50, s36
	s_addc_u32 s41, s51, 0
	s_lshl_b32 s36, s30, 8
	s_add_u32 s36, s36, 0xc380000
	s_add_u32 s6, s48, s36
	s_addc_u32 s7, s49, 0

.Lat_nosq1:
.Lat_item_nofetch:
	v_mov_b32_e32 v2, 0
	v_mov_b32_e32 v3, 0
	v_mov_b32_e32 v4, 0
	v_mov_b32_e32 v5, 0
	v_mov_b32_e32 v6, 0
	v_mov_b32_e32 v7, 0
	v_mov_b32_e32 v8, 0
	v_mov_b32_e32 v9, 0
	v_mov_b32_e32 v10, 0
	v_mov_b32_e32 v11, 0
	v_mov_b32_e32 v12, 0
	v_mov_b32_e32 v13, 0
	v_mov_b32_e32 v14, 0
	v_mov_b32_e32 v15, 0
	v_mov_b32_e32 v16, 0
	v_mov_b32_e32 v17, 0
	v_mov_b32_e32 v18, 0
	v_mov_b32_e32 v19, 0
	v_mov_b32_e32 v20, 0
	v_mov_b32_e32 v21, 0
	v_mov_b32_e32 v22, 0
	v_mov_b32_e32 v23, 0
	v_mov_b32_e32 v24, 0
	v_mov_b32_e32 v25, 0
	v_mov_b32_e32 v26, 0
	v_mov_b32_e32 v27, 0
	v_mov_b32_e32 v28, 0
	v_mov_b32_e32 v29, 0
	v_mov_b32_e32 v30, 0
	v_mov_b32_e32 v31, 0
	v_mov_b32_e32 v32, 0
	v_mov_b32_e32 v33, 0
	v_mov_b32_e32 v34, 0
	v_mov_b32_e32 v35, 0
	v_mov_b32_e32 v36, 0
	v_mov_b32_e32 v37, 0
	v_mov_b32_e32 v38, 0
	v_mov_b32_e32 v39, 0
	v_mov_b32_e32 v40, 0
	v_mov_b32_e32 v41, 0
	v_mov_b32_e32 v42, 0
	v_mov_b32_e32 v43, 0
	v_mov_b32_e32 v44, 0
	v_mov_b32_e32 v45, 0
	v_mov_b32_e32 v46, 0
	v_mov_b32_e32 v47, 0
	v_mov_b32_e32 v48, 0
	v_mov_b32_e32 v49, 0
	v_mov_b32_e32 v50, 0
	v_mov_b32_e32 v51, 0
	v_mov_b32_e32 v52, 0
	v_mov_b32_e32 v53, 0
	v_mov_b32_e32 v54, 0
	v_mov_b32_e32 v55, 0
	v_mov_b32_e32 v56, 0
	v_mov_b32_e32 v57, 0
	v_mov_b32_e32 v58, 0
	v_mov_b32_e32 v59, 0
	v_mov_b32_e32 v60, 0
	v_mov_b32_e32 v61, 0
	v_mov_b32_e32 v62, 0
	v_mov_b32_e32 v63, 0
	v_mov_b32_e32 v64, 0
	v_mov_b32_e32 v65, 0
	v_mov_b32_e32 v236, v238
	v_mov_b32_e32 v237, 0
	s_cmp_lg_u32 s26, 0
	s_cbranch_scc1 .Lat_item_nobar
	s_barrier

.Lat_nosq6:
.Lat_x_nopf:
	s_barrier
	s_cmp_gt_i32 s22, s25
	s_cbranch_scc1 .Lat_y_done
	s_setprio 0
	s_nop 7
	s_waitcnt lgkmcnt(0)
	v_mul_f32_e32 v66, v66, v162
	v_mul_f32_e32 v67, v67, v163
	v_mul_f32_e32 v68, v68, v164
	v_mul_f32_e32 v69, v69, v165
	v_mul_f32_e32 v70, v70, v166
	v_mul_f32_e32 v71, v71, v167
	v_mul_f32_e32 v72, v72, v168
	v_mul_f32_e32 v73, v73, v169
	v_mul_f32_e32 v74, v74, v170
	v_mul_f32_e32 v75, v75, v171
	v_mul_f32_e32 v76, v76, v172
	v_mul_f32_e32 v77, v77, v173
	v_mul_f32_e32 v78, v78, v174
	v_mul_f32_e32 v79, v79, v175
	v_mul_f32_e32 v80, v80, v176
	v_mul_f32_e32 v81, v81, v177
	v_mul_f32_e32 v82, v82, v178
	v_mul_f32_e32 v83, v83, v179
	v_mul_f32_e32 v84, v84, v180
	v_mul_f32_e32 v85, v85, v181
	v_mul_f32_e32 v86, v86, v182
	v_mul_f32_e32 v87, v87, v183
	v_mul_f32_e32 v88, v88, v184
	v_mul_f32_e32 v89, v89, v185
	v_mul_f32_e32 v90, v90, v186
	v_mul_f32_e32 v91, v91, v187
	v_mul_f32_e32 v92, v92, v188
	v_mul_f32_e32 v93, v93, v189
	v_mul_f32_e32 v94, v94, v190
	v_mul_f32_e32 v95, v95, v191
	v_mul_f32_e32 v96, v96, v192
	v_mul_f32_e32 v97, v97, v193
	s_cmp_lg_u32 s22, s25
	s_cbranch_scc1 .Lat_y_nogate
	v_add_u32_e32 v194, s38, v234
	v_lshlrev_b32_e32 v194, 11, v194
	v_lshl_add_u32 v194, v241, 3, v194
	global_load_dwordx2 v[162:163], v194, s[6:7] offset:0
	global_load_dwordx2 v[164:165], v194, s[6:7] offset:16
	global_load_dwordx2 v[166:167], v194, s[6:7] offset:32
	global_load_dwordx2 v[168:169], v194, s[6:7] offset:48
	global_load_dwordx2 v[170:171], v194, s[6:7] offset:64
	global_load_dwordx2 v[172:173], v194, s[6:7] offset:80
	global_load_dwordx2 v[174:175], v194, s[6:7] offset:96
	global_load_dwordx2 v[176:177], v194, s[6:7] offset:112
	global_load_dwordx2 v[178:179], v194, s[6:7] offset:128
	global_load_dwordx2 v[180:181], v194, s[6:7] offset:144
	global_load_dwordx2 v[182:183], v194, s[6:7] offset:160
	global_load_dwordx2 v[184:185], v194, s[6:7] offset:176
	global_load_dwordx2 v[186:187], v194, s[6:7] offset:192
	global_load_dwordx2 v[188:189], v194, s[6:7] offset:208
	global_load_dwordx2 v[190:191], v194, s[6:7] offset:224
	global_load_dwordx2 v[192:193], v194, s[6:7] offset:240

.Lat_y_done:
	s_setprio 1
	s_barrier

.Lat_all_done:
	s_setprio 0
	s_waitcnt vmcnt(0)
	s_branch .LBB0_384
